# UP epilogue: conv-weight loads hoisted before side-buffer stores, LDS-only wait before the barrier, counted vmcnt so no wave waits on its RAW stores
# speedup vs baseline: 1.0162x; 1.0046x over previous
.LBB0_318:
	v_mov_b32_e32 v184, v188
	v_mov_b32_e32 v192, v189
	s_nop 0
	v_lshl_add_u32 v186, v192, 3, s44
	v_cmp_lt_i32_e32 vcc, 13, v184
	s_and_saveexec_b64 s[0:1], vcc
	s_cbranch_execz .LBB0_320
	v_lshlrev_b32_e32 v0, 2, v186
	v_lshlrev_b32_e32 v154, 9, v184
	v_add3_u32 v0, s66, v0, v154
	v_add_u32_e32 v154, 0xffffec10, v0
	v_add_u32_e32 v155, 0xffffec00, v0
	v_add_u32_e32 v156, 0xffffe410, v0
	v_add_u32_e32 v0, 0xffffe400, v0
	ds_write_b128 v0, v[102:105]
	ds_write_b128 v156, v[98:101]
	ds_write_b128 v155, v[38:41]
	ds_write_b128 v154, v[34:37]
.LBB0_320:
	s_or_b64 exec, exec, s[0:1]
	s_lshl_b32 s0, s69, 2
	v_readlane_b32 s2, v253, 22
	s_add_i32 s4, s0, s2
	v_readlane_b32 s3, v253, 23
	s_cmp_lt_i32 s4, 22
	s_cselect_b64 s[2:3], -1, 0
	s_and_b64 s[0:1], s[2:3], exec
	v_readlane_b32 s0, v253, 25
	s_cselect_b32 s68, s4, s68
	v_readlane_b32 s1, v253, 26
	s_cselect_b32 s54, s0, s54
	s_and_b64 s[4:5], s[28:29], vcc
	v_ashrrev_i32_e32 v187, 31, v186
	s_lshl_b32 s6, s68, 7
	s_ashr_i32 s7, s6, 31
	s_lshl_b64 s[6:7], s[6:7], 2
	s_add_u32 s6, s30, s6
	s_addc_u32 s7, s31, s7
	v_lshl_add_u64 v[138:139], v[186:187], 2, s[6:7]
	s_mov_b64 s[0:1], 0x2c00
	v_add_co_u32_e32 v136, vcc, 0x2000, v138
	v_lshl_add_u64 v[134:135], v[138:139], 0, s[0:1]
	s_nop 0
	v_addc_co_u32_e32 v137, vcc, 0, v139, vcc
	s_mov_b64 s[0:1], 0x5800
	global_load_dwordx4 v[130:133], v[138:139], off offset:16
	global_load_dwordx4 v[142:145], v[138:139], off
	v_lshl_add_u64 v[140:141], v[138:139], 0, s[0:1]
	v_add_co_u32_e32 v138, vcc, 0x5000, v138
	global_load_dwordx4 v[146:149], v[136:137], off offset:3072
	s_nop 0
	global_load_dwordx4 v[134:137], v[134:135], off offset:16
	v_addc_co_u32_e32 v139, vcc, 0, v139, vcc
	global_load_dwordx4 v[150:153], v[138:139], off offset:2048
	s_nop 0
	global_load_dwordx4 v[138:141], v[140:141], off offset:16
	s_and_saveexec_b64 s[0:1], s[4:5]
	s_cbranch_execz .LBB0_322
	s_ashr_i32 s55, s54, 31
	v_add_u32_e32 v0, -14, v184
	v_lshl_add_u64 v[154:155], s[54:55], 1, v[0:1]
	v_mov_b64_e32 v[156:157], s[48:49]
	s_movk_i32 s6, 0x2c00
	v_mad_u64_u32 v[156:157], s[4:5], v154, s6, v[156:157]
	s_lshl_b32 s4, s68, 7
	v_mad_i32_i24 v157, v155, s6, v157
	s_ashr_i32 s5, s4, 31
	v_lshl_add_u64 v[154:155], s[4:5], 2, v[156:157]
	v_lshl_add_u64 v[154:155], v[186:187], 2, v[154:155]
	global_store_dwordx4 v[154:155], v[38:41], off
	global_store_dwordx4 v[154:155], v[34:37], off offset:16
.LBB0_322:
	s_or_b64 exec, exec, s[0:1]
	v_cmp_lt_i32_e32 vcc, 1, v184
	s_xor_b64 s[0:1], s[36:37], -1
	s_or_b64 s[0:1], s[0:1], vcc
	s_and_saveexec_b64 s[4:5], s[0:1]
	s_xor_b64 s[0:1], exec, s[4:5]
	s_lshl_b32 s4, s68, 7
	s_ashr_i32 s5, s4, 31
	v_mov_b64_e32 v[182:183], s[4:5]
	s_andn2_saveexec_b64 s[0:1], s[0:1]
	s_cbranch_execz .LBB0_326
	s_ashr_i32 s55, s54, 31
	v_ashrrev_i32_e32 v185, 31, v184
	v_lshl_add_u64 v[154:155], s[54:55], 1, v[184:185]
	v_mov_b64_e32 v[156:157], s[10:11]
	s_movk_i32 s6, 0x5800
	v_mad_u64_u32 v[156:157], s[4:5], v154, s6, v[156:157]
	s_lshl_b32 s4, s68, 7
	v_mad_i32_i24 v157, v155, s6, v157
	s_ashr_i32 s5, s4, 31
	v_lshl_add_u64 v[154:155], s[4:5], 2, v[156:157]
	v_lshl_add_u64 v[154:155], v[186:187], 2, v[154:155]
	global_store_dwordx4 v[154:155], v[126:129], off
	global_store_dwordx4 v[154:155], v[122:125], off offset:16
	v_add_co_u32_e32 v154, vcc, 0x2000, v154
	v_mov_b64_e32 v[182:183], s[4:5]
	s_nop 0
	v_addc_co_u32_e32 v155, vcc, 0, v155, vcc
	global_store_dwordx4 v[154:155], v[94:97], off offset:3072
	global_store_dwordx4 v[154:155], v[90:93], off offset:3088
.LBB0_326:
	s_or_b64 exec, exec, s[0:1]
	s_waitcnt lgkmcnt(0)
	s_barrier
	s_and_b64 s[0:1], s[2:3], exec
	s_cselect_b32 s53, s65, s53
	s_cselect_b32 s52, s64, s52
	v_lshl_add_u32 v0, v186, 2, s67
	v_lshl_add_u32 v228, v186, 2, s66
	s_andn2_b64 vcc, exec, s[38:39]
	s_cbranch_vccnz .Lffn_z0
	ds_read_b128 v[200:203], v0
	ds_read_b128 v[192:195], v0 offset:512
	ds_read_b128 v[204:207], v0 offset:16
	ds_read_b128 v[196:199], v0 offset:528
	s_branch .Lffn_d0

.Lffn_d0:
	v_add_u32_e32 v230, s41, v184
	s_lshl_b32 s6, s54, 8
	v_add_u32_e32 v230, s6, v230
	v_mov_b64_e32 v[158:159], s[52:53]
	s_movk_i32 s6, 0x1600
	v_mad_i64_i32 v[158:159], s[8:9], v230, s6, v[158:159]
	v_lshl_add_u64 v[158:159], v[182:183], 1, v[158:159]
	v_lshl_add_u64 v[158:159], v[186:187], 1, v[158:159]
	s_mov_b32 s6, 0x16000
	s_mov_b32 s7, 0
	s_mov_b32 s2, 0xbfb8aa3b
	s_mov_b32 s3, 1.0
	v_cmp_eq_u32_e64 s[4:5], 0, v184
	v_cmp_lt_i32_e64 s[0:1], 0, v184
	v_cmp_lt_i32_e64 s[8:9], 1, v184
	s_and_b64 vcc, exec, s[36:37]
	s_cbranch_vccz .Lffn_w1
	s_waitcnt vmcnt(4) lgkmcnt(0)
	s_branch .Lffn_wd
.Lffn_w1:
	s_waitcnt vmcnt(2) lgkmcnt(0)
.Lffn_wd:
	v_cndmask_b32_e64 v200, v192, v200, s[4:5]
	v_cndmask_b32_e64 v201, v193, v201, s[4:5]
	v_cndmask_b32_e64 v202, v194, v202, s[4:5]
	v_cndmask_b32_e64 v203, v195, v203, s[4:5]
	v_cndmask_b32_e64 v204, v196, v204, s[4:5]
	v_cndmask_b32_e64 v205, v197, v205, s[4:5]
	v_cndmask_b32_e64 v206, v198, v206, s[4:5]
	v_cndmask_b32_e64 v207, v199, v207, s[4:5]
	v_mov_b32_dpp v208, v126 row_ror:1 row_mask:0xf bank_mask:0xf
	v_mov_b32_dpp v209, v127 row_ror:1 row_mask:0xf bank_mask:0xf
	v_mov_b32_dpp v210, v128 row_ror:1 row_mask:0xf bank_mask:0xf
	v_mov_b32_dpp v211, v129 row_ror:1 row_mask:0xf bank_mask:0xf
	v_mov_b32_dpp v212, v122 row_ror:1 row_mask:0xf bank_mask:0xf
	v_mov_b32_dpp v213, v123 row_ror:1 row_mask:0xf bank_mask:0xf
	v_mov_b32_dpp v214, v124 row_ror:1 row_mask:0xf bank_mask:0xf
	v_mov_b32_dpp v215, v125 row_ror:1 row_mask:0xf bank_mask:0xf
	v_mov_b32_dpp v160, v126 row_ror:2 row_mask:0xf bank_mask:0xf
	v_mov_b32_dpp v161, v127 row_ror:2 row_mask:0xf bank_mask:0xf
	v_mov_b32_dpp v162, v128 row_ror:2 row_mask:0xf bank_mask:0xf
	v_mov_b32_dpp v163, v129 row_ror:2 row_mask:0xf bank_mask:0xf
	v_mov_b32_dpp v164, v122 row_ror:2 row_mask:0xf bank_mask:0xf
	v_mov_b32_dpp v165, v123 row_ror:2 row_mask:0xf bank_mask:0xf
	v_mov_b32_dpp v166, v124 row_ror:2 row_mask:0xf bank_mask:0xf
	v_mov_b32_dpp v167, v125 row_ror:2 row_mask:0xf bank_mask:0xf
	v_cndmask_b32_e64 v192, v192, v208, s[0:1]
	v_cndmask_b32_e64 v193, v193, v209, s[0:1]
	v_cndmask_b32_e64 v194, v194, v210, s[0:1]
	v_cndmask_b32_e64 v195, v195, v211, s[0:1]
	v_cndmask_b32_e64 v196, v196, v212, s[0:1]
	v_cndmask_b32_e64 v197, v197, v213, s[0:1]
	v_cndmask_b32_e64 v198, v198, v214, s[0:1]
	v_cndmask_b32_e64 v199, v199, v215, s[0:1]
	v_cndmask_b32_e64 v200, v200, v160, s[8:9]
	v_cndmask_b32_e64 v201, v201, v161, s[8:9]
	v_cndmask_b32_e64 v202, v202, v162, s[8:9]
	v_cndmask_b32_e64 v203, v203, v163, s[8:9]
	v_cndmask_b32_e64 v204, v204, v164, s[8:9]
	v_cndmask_b32_e64 v205, v205, v165, s[8:9]
	v_cndmask_b32_e64 v206, v206, v166, s[8:9]
	v_cndmask_b32_e64 v207, v207, v167, s[8:9]
	v_pk_mul_f32 v[192:193], v[146:147], v[192:193]
	v_pk_mul_f32 v[194:195], v[148:149], v[194:195]
	v_pk_mul_f32 v[196:197], v[134:135], v[196:197]
	v_pk_mul_f32 v[198:199], v[136:137], v[198:199]
	v_pk_mul_f32 v[168:169], v[126:127], v[150:151]
	v_pk_mul_f32 v[182:183], v[128:129], v[152:153]
	v_pk_mul_f32 v[184:185], v[122:123], v[138:139]
	v_pk_mul_f32 v[186:187], v[124:125], v[140:141]
	v_pk_fma_f32 v[200:201], v[142:143], v[200:201], v[192:193]
	v_pk_fma_f32 v[202:203], v[144:145], v[202:203], v[194:195]
	v_pk_fma_f32 v[204:205], v[130:131], v[204:205], v[196:197]
	v_pk_fma_f32 v[206:207], v[132:133], v[206:207], v[198:199]
	v_pk_add_f32 v[168:169], v[168:169], v[200:201]
	v_pk_add_f32 v[182:183], v[182:183], v[202:203]
	v_pk_add_f32 v[184:185], v[184:185], v[204:205]
	v_pk_add_f32 v[186:187], v[186:187], v[206:207]
	v_pk_mul_f32 v[200:201], v[168:169], s[2:3] op_sel_hi:[1,0]
	v_pk_mul_f32 v[202:203], v[182:183], s[2:3] op_sel_hi:[1,0]
	v_pk_mul_f32 v[204:205], v[184:185], s[2:3] op_sel_hi:[1,0]
	v_pk_mul_f32 v[206:207], v[186:187], s[2:3] op_sel_hi:[1,0]
	v_exp_f32_e32 v200, v200
	v_exp_f32_e32 v201, v201
	v_exp_f32_e32 v202, v202
	v_exp_f32_e32 v203, v203
	v_exp_f32_e32 v204, v204
	v_exp_f32_e32 v205, v205
	v_exp_f32_e32 v206, v206
	v_exp_f32_e32 v207, v207
	v_pk_add_f32 v[200:201], v[200:201], s[2:3] op_sel:[0,1] op_sel_hi:[1,1]
	v_pk_add_f32 v[202:203], v[202:203], s[2:3] op_sel:[0,1] op_sel_hi:[1,1]
	v_pk_add_f32 v[204:205], v[204:205], s[2:3] op_sel:[0,1] op_sel_hi:[1,1]
	v_pk_add_f32 v[206:207], v[206:207], s[2:3] op_sel:[0,1] op_sel_hi:[1,1]
	v_rcp_f32_e32 v200, v200
	v_rcp_f32_e32 v201, v201
	v_rcp_f32_e32 v202, v202
	v_rcp_f32_e32 v203, v203
	v_rcp_f32_e32 v204, v204
	v_rcp_f32_e32 v205, v205
	v_rcp_f32_e32 v206, v206
	v_rcp_f32_e32 v207, v207
	v_pk_mul_f32 v[168:169], v[168:169], v[200:201]
	v_pk_mul_f32 v[182:183], v[182:183], v[202:203]
	v_pk_mul_f32 v[184:185], v[184:185], v[204:205]
	v_pk_mul_f32 v[186:187], v[186:187], v[206:207]
	v_pk_mul_f32 v[168:169], v[94:95], v[168:169]
	v_pk_mul_f32 v[182:183], v[96:97], v[182:183]
	v_pk_mul_f32 v[184:185], v[90:91], v[184:185]
	v_pk_mul_f32 v[186:187], v[92:93], v[186:187]
	v_cvt_pk_bf16_f32 v154, v168, v169
	v_cvt_pk_bf16_f32 v155, v182, v183
	v_cvt_pk_bf16_f32 v156, v184, v185
	v_cvt_pk_bf16_f32 v157, v186, v187
	flat_store_dwordx4 v[158:159], v[154:157]
	v_lshl_add_u64 v[158:159], v[158:159], 0, s[6:7]
	v_mov_b32_dpp v192, v118 row_ror:1 row_mask:0xf bank_mask:0xf
	v_mov_b32_dpp v193, v119 row_ror:1 row_mask:0xf bank_mask:0xf
	v_mov_b32_dpp v194, v120 row_ror:1 row_mask:0xf bank_mask:0xf
	v_mov_b32_dpp v195, v121 row_ror:1 row_mask:0xf bank_mask:0xf
	v_mov_b32_dpp v196, v114 row_ror:1 row_mask:0xf bank_mask:0xf
	v_mov_b32_dpp v197, v115 row_ror:1 row_mask:0xf bank_mask:0xf
	v_mov_b32_dpp v198, v116 row_ror:1 row_mask:0xf bank_mask:0xf
	v_mov_b32_dpp v199, v117 row_ror:1 row_mask:0xf bank_mask:0xf
	v_mov_b32_dpp v200, v118 row_ror:2 row_mask:0xf bank_mask:0xf
	v_mov_b32_dpp v201, v119 row_ror:2 row_mask:0xf bank_mask:0xf
	v_mov_b32_dpp v202, v120 row_ror:2 row_mask:0xf bank_mask:0xf
	v_mov_b32_dpp v203, v121 row_ror:2 row_mask:0xf bank_mask:0xf
	v_mov_b32_dpp v204, v114 row_ror:2 row_mask:0xf bank_mask:0xf
	v_mov_b32_dpp v205, v115 row_ror:2 row_mask:0xf bank_mask:0xf
	v_mov_b32_dpp v206, v116 row_ror:2 row_mask:0xf bank_mask:0xf
	v_mov_b32_dpp v207, v117 row_ror:2 row_mask:0xf bank_mask:0xf
	v_cndmask_b32_e64 v208, v208, v192, s[0:1]
	v_cndmask_b32_e64 v209, v209, v193, s[0:1]
	v_cndmask_b32_e64 v210, v210, v194, s[0:1]
	v_cndmask_b32_e64 v211, v211, v195, s[0:1]
	v_cndmask_b32_e64 v212, v212, v196, s[0:1]
	v_cndmask_b32_e64 v213, v213, v197, s[0:1]
	v_cndmask_b32_e64 v214, v214, v198, s[0:1]
	v_cndmask_b32_e64 v215, v215, v199, s[0:1]
	v_cndmask_b32_e64 v160, v160, v200, s[8:9]
	v_cndmask_b32_e64 v161, v161, v201, s[8:9]
	v_cndmask_b32_e64 v162, v162, v202, s[8:9]
	v_cndmask_b32_e64 v163, v163, v203, s[8:9]
	v_cndmask_b32_e64 v164, v164, v204, s[8:9]
	v_cndmask_b32_e64 v165, v165, v205, s[8:9]
	v_cndmask_b32_e64 v166, v166, v206, s[8:9]
	v_cndmask_b32_e64 v167, v167, v207, s[8:9]
	v_pk_mul_f32 v[208:209], v[146:147], v[208:209]
	v_pk_mul_f32 v[210:211], v[148:149], v[210:211]
	v_pk_mul_f32 v[212:213], v[134:135], v[212:213]
	v_pk_mul_f32 v[214:215], v[136:137], v[214:215]
	v_pk_mul_f32 v[168:169], v[118:119], v[150:151]
	v_pk_mul_f32 v[182:183], v[120:121], v[152:153]
	v_pk_mul_f32 v[184:185], v[114:115], v[138:139]
	v_pk_mul_f32 v[186:187], v[116:117], v[140:141]
	v_pk_fma_f32 v[160:161], v[142:143], v[160:161], v[208:209]
	v_pk_fma_f32 v[162:163], v[144:145], v[162:163], v[210:211]
	v_pk_fma_f32 v[164:165], v[130:131], v[164:165], v[212:213]
	v_pk_fma_f32 v[166:167], v[132:133], v[166:167], v[214:215]
	v_pk_add_f32 v[168:169], v[168:169], v[160:161]
	v_pk_add_f32 v[182:183], v[182:183], v[162:163]
	v_pk_add_f32 v[184:185], v[184:185], v[164:165]
	v_pk_add_f32 v[186:187], v[186:187], v[166:167]
	v_pk_mul_f32 v[160:161], v[168:169], s[2:3] op_sel_hi:[1,0]
	v_pk_mul_f32 v[162:163], v[182:183], s[2:3] op_sel_hi:[1,0]
	v_pk_mul_f32 v[164:165], v[184:185], s[2:3] op_sel_hi:[1,0]
	v_pk_mul_f32 v[166:167], v[186:187], s[2:3] op_sel_hi:[1,0]
	v_exp_f32_e32 v160, v160
	v_exp_f32_e32 v161, v161
	v_exp_f32_e32 v162, v162
	v_exp_f32_e32 v163, v163
	v_exp_f32_e32 v164, v164
	v_exp_f32_e32 v165, v165
	v_exp_f32_e32 v166, v166
	v_exp_f32_e32 v167, v167
	v_pk_add_f32 v[160:161], v[160:161], s[2:3] op_sel:[0,1] op_sel_hi:[1,1]
	v_pk_add_f32 v[162:163], v[162:163], s[2:3] op_sel:[0,1] op_sel_hi:[1,1]
	v_pk_add_f32 v[164:165], v[164:165], s[2:3] op_sel:[0,1] op_sel_hi:[1,1]
	v_pk_add_f32 v[166:167], v[166:167], s[2:3] op_sel:[0,1] op_sel_hi:[1,1]
	v_rcp_f32_e32 v160, v160
	v_rcp_f32_e32 v161, v161
	v_rcp_f32_e32 v162, v162
	v_rcp_f32_e32 v163, v163
	v_rcp_f32_e32 v164, v164
	v_rcp_f32_e32 v165, v165
	v_rcp_f32_e32 v166, v166
	v_rcp_f32_e32 v167, v167
	v_pk_mul_f32 v[168:169], v[168:169], v[160:161]
	v_pk_mul_f32 v[182:183], v[182:183], v[162:163]
	v_pk_mul_f32 v[184:185], v[184:185], v[164:165]
	v_pk_mul_f32 v[186:187], v[186:187], v[166:167]
	v_pk_mul_f32 v[168:169], v[86:87], v[168:169]
	v_pk_mul_f32 v[182:183], v[88:89], v[182:183]
	v_pk_mul_f32 v[184:185], v[82:83], v[184:185]
	v_pk_mul_f32 v[186:187], v[84:85], v[186:187]
	v_cvt_pk_bf16_f32 v154, v168, v169
	v_cvt_pk_bf16_f32 v155, v182, v183
	v_cvt_pk_bf16_f32 v156, v184, v185
	v_cvt_pk_bf16_f32 v157, v186, v187
	flat_store_dwordx4 v[158:159], v[154:157]
	v_lshl_add_u64 v[158:159], v[158:159], 0, s[6:7]
	v_mov_b32_dpp v208, v110 row_ror:1 row_mask:0xf bank_mask:0xf
	v_mov_b32_dpp v209, v111 row_ror:1 row_mask:0xf bank_mask:0xf
	v_mov_b32_dpp v210, v112 row_ror:1 row_mask:0xf bank_mask:0xf
	v_mov_b32_dpp v211, v113 row_ror:1 row_mask:0xf bank_mask:0xf
	v_mov_b32_dpp v212, v106 row_ror:1 row_mask:0xf bank_mask:0xf
	v_mov_b32_dpp v213, v107 row_ror:1 row_mask:0xf bank_mask:0xf
	v_mov_b32_dpp v214, v108 row_ror:1 row_mask:0xf bank_mask:0xf
	v_mov_b32_dpp v215, v109 row_ror:1 row_mask:0xf bank_mask:0xf
	v_mov_b32_dpp v160, v110 row_ror:2 row_mask:0xf bank_mask:0xf
	v_mov_b32_dpp v161, v111 row_ror:2 row_mask:0xf bank_mask:0xf
	v_mov_b32_dpp v162, v112 row_ror:2 row_mask:0xf bank_mask:0xf
	v_mov_b32_dpp v163, v113 row_ror:2 row_mask:0xf bank_mask:0xf
	v_mov_b32_dpp v164, v106 row_ror:2 row_mask:0xf bank_mask:0xf
	v_mov_b32_dpp v165, v107 row_ror:2 row_mask:0xf bank_mask:0xf
	v_mov_b32_dpp v166, v108 row_ror:2 row_mask:0xf bank_mask:0xf
	v_mov_b32_dpp v167, v109 row_ror:2 row_mask:0xf bank_mask:0xf
	v_cndmask_b32_e64 v192, v192, v208, s[0:1]
	v_cndmask_b32_e64 v193, v193, v209, s[0:1]
	v_cndmask_b32_e64 v194, v194, v210, s[0:1]
	v_cndmask_b32_e64 v195, v195, v211, s[0:1]
	v_cndmask_b32_e64 v196, v196, v212, s[0:1]
	v_cndmask_b32_e64 v197, v197, v213, s[0:1]
	v_cndmask_b32_e64 v198, v198, v214, s[0:1]
	v_cndmask_b32_e64 v199, v199, v215, s[0:1]
	v_cndmask_b32_e64 v200, v200, v160, s[8:9]
	v_cndmask_b32_e64 v201, v201, v161, s[8:9]
	v_cndmask_b32_e64 v202, v202, v162, s[8:9]
	v_cndmask_b32_e64 v203, v203, v163, s[8:9]
	v_cndmask_b32_e64 v204, v204, v164, s[8:9]
	v_cndmask_b32_e64 v205, v205, v165, s[8:9]
	v_cndmask_b32_e64 v206, v206, v166, s[8:9]
	v_cndmask_b32_e64 v207, v207, v167, s[8:9]
	v_pk_mul_f32 v[192:193], v[146:147], v[192:193]
	v_pk_mul_f32 v[194:195], v[148:149], v[194:195]
	v_pk_mul_f32 v[196:197], v[134:135], v[196:197]
	v_pk_mul_f32 v[198:199], v[136:137], v[198:199]
	v_pk_mul_f32 v[168:169], v[110:111], v[150:151]
	v_pk_mul_f32 v[182:183], v[112:113], v[152:153]
	v_pk_mul_f32 v[184:185], v[106:107], v[138:139]
	v_pk_mul_f32 v[186:187], v[108:109], v[140:141]
	v_pk_fma_f32 v[200:201], v[142:143], v[200:201], v[192:193]
	v_pk_fma_f32 v[202:203], v[144:145], v[202:203], v[194:195]
	v_pk_fma_f32 v[204:205], v[130:131], v[204:205], v[196:197]
	v_pk_fma_f32 v[206:207], v[132:133], v[206:207], v[198:199]
	v_pk_add_f32 v[168:169], v[168:169], v[200:201]
	v_pk_add_f32 v[182:183], v[182:183], v[202:203]
	v_pk_add_f32 v[184:185], v[184:185], v[204:205]
	v_pk_add_f32 v[186:187], v[186:187], v[206:207]
	v_pk_mul_f32 v[200:201], v[168:169], s[2:3] op_sel_hi:[1,0]
	v_pk_mul_f32 v[202:203], v[182:183], s[2:3] op_sel_hi:[1,0]
	v_pk_mul_f32 v[204:205], v[184:185], s[2:3] op_sel_hi:[1,0]
	v_pk_mul_f32 v[206:207], v[186:187], s[2:3] op_sel_hi:[1,0]
	v_exp_f32_e32 v200, v200
	v_exp_f32_e32 v201, v201
	v_exp_f32_e32 v202, v202
	v_exp_f32_e32 v203, v203
	v_exp_f32_e32 v204, v204
	v_exp_f32_e32 v205, v205
	v_exp_f32_e32 v206, v206
	v_exp_f32_e32 v207, v207
	v_pk_add_f32 v[200:201], v[200:201], s[2:3] op_sel:[0,1] op_sel_hi:[1,1]
	v_pk_add_f32 v[202:203], v[202:203], s[2:3] op_sel:[0,1] op_sel_hi:[1,1]
	v_pk_add_f32 v[204:205], v[204:205], s[2:3] op_sel:[0,1] op_sel_hi:[1,1]
	v_pk_add_f32 v[206:207], v[206:207], s[2:3] op_sel:[0,1] op_sel_hi:[1,1]
	v_rcp_f32_e32 v200, v200
	v_rcp_f32_e32 v201, v201
	v_rcp_f32_e32 v202, v202
	v_rcp_f32_e32 v203, v203
	v_rcp_f32_e32 v204, v204
	v_rcp_f32_e32 v205, v205
	v_rcp_f32_e32 v206, v206
	v_rcp_f32_e32 v207, v207
	v_pk_mul_f32 v[168:169], v[168:169], v[200:201]
	v_pk_mul_f32 v[182:183], v[182:183], v[202:203]
	v_pk_mul_f32 v[184:185], v[184:185], v[204:205]
	v_pk_mul_f32 v[186:187], v[186:187], v[206:207]
	v_pk_mul_f32 v[168:169], v[78:79], v[168:169]
	v_pk_mul_f32 v[182:183], v[80:81], v[182:183]
	v_pk_mul_f32 v[184:185], v[74:75], v[184:185]
	v_pk_mul_f32 v[186:187], v[76:77], v[186:187]
	v_cvt_pk_bf16_f32 v154, v168, v169
	v_cvt_pk_bf16_f32 v155, v182, v183
	v_cvt_pk_bf16_f32 v156, v184, v185
	v_cvt_pk_bf16_f32 v157, v186, v187
	flat_store_dwordx4 v[158:159], v[154:157]
	v_lshl_add_u64 v[158:159], v[158:159], 0, s[6:7]
	v_mov_b32_dpp v192, v102 row_ror:1 row_mask:0xf bank_mask:0xf
	v_mov_b32_dpp v193, v103 row_ror:1 row_mask:0xf bank_mask:0xf
	v_mov_b32_dpp v194, v104 row_ror:1 row_mask:0xf bank_mask:0xf
	v_mov_b32_dpp v195, v105 row_ror:1 row_mask:0xf bank_mask:0xf
	v_mov_b32_dpp v196, v98 row_ror:1 row_mask:0xf bank_mask:0xf
	v_mov_b32_dpp v197, v99 row_ror:1 row_mask:0xf bank_mask:0xf
	v_mov_b32_dpp v198, v100 row_ror:1 row_mask:0xf bank_mask:0xf
	v_mov_b32_dpp v199, v101 row_ror:1 row_mask:0xf bank_mask:0xf
	v_mov_b32_dpp v200, v102 row_ror:2 row_mask:0xf bank_mask:0xf
	v_mov_b32_dpp v201, v103 row_ror:2 row_mask:0xf bank_mask:0xf
	v_mov_b32_dpp v202, v104 row_ror:2 row_mask:0xf bank_mask:0xf
	v_mov_b32_dpp v203, v105 row_ror:2 row_mask:0xf bank_mask:0xf
	v_mov_b32_dpp v204, v98 row_ror:2 row_mask:0xf bank_mask:0xf
	v_mov_b32_dpp v205, v99 row_ror:2 row_mask:0xf bank_mask:0xf
	v_mov_b32_dpp v206, v100 row_ror:2 row_mask:0xf bank_mask:0xf
	v_mov_b32_dpp v207, v101 row_ror:2 row_mask:0xf bank_mask:0xf
	v_cndmask_b32_e64 v208, v208, v192, s[0:1]
	v_cndmask_b32_e64 v209, v209, v193, s[0:1]
	v_cndmask_b32_e64 v210, v210, v194, s[0:1]
	v_cndmask_b32_e64 v211, v211, v195, s[0:1]
	v_cndmask_b32_e64 v212, v212, v196, s[0:1]
	v_cndmask_b32_e64 v213, v213, v197, s[0:1]
	v_cndmask_b32_e64 v214, v214, v198, s[0:1]
	v_cndmask_b32_e64 v215, v215, v199, s[0:1]
	v_cndmask_b32_e64 v160, v160, v200, s[8:9]
	v_cndmask_b32_e64 v161, v161, v201, s[8:9]
	v_cndmask_b32_e64 v162, v162, v202, s[8:9]
	v_cndmask_b32_e64 v163, v163, v203, s[8:9]
	v_cndmask_b32_e64 v164, v164, v204, s[8:9]
	v_cndmask_b32_e64 v165, v165, v205, s[8:9]
	v_cndmask_b32_e64 v166, v166, v206, s[8:9]
	v_cndmask_b32_e64 v167, v167, v207, s[8:9]
	v_pk_mul_f32 v[208:209], v[146:147], v[208:209]
	v_pk_mul_f32 v[210:211], v[148:149], v[210:211]
	v_pk_mul_f32 v[212:213], v[134:135], v[212:213]
	v_pk_mul_f32 v[214:215], v[136:137], v[214:215]
	v_pk_mul_f32 v[168:169], v[102:103], v[150:151]
	v_pk_mul_f32 v[182:183], v[104:105], v[152:153]
	v_pk_mul_f32 v[184:185], v[98:99], v[138:139]
	v_pk_mul_f32 v[186:187], v[100:101], v[140:141]
	v_pk_fma_f32 v[160:161], v[142:143], v[160:161], v[208:209]
	v_pk_fma_f32 v[162:163], v[144:145], v[162:163], v[210:211]
	v_pk_fma_f32 v[164:165], v[130:131], v[164:165], v[212:213]
	v_pk_fma_f32 v[166:167], v[132:133], v[166:167], v[214:215]
	v_pk_add_f32 v[168:169], v[168:169], v[160:161]
	v_pk_add_f32 v[182:183], v[182:183], v[162:163]
	v_pk_add_f32 v[184:185], v[184:185], v[164:165]
	v_pk_add_f32 v[186:187], v[186:187], v[166:167]
	v_pk_mul_f32 v[160:161], v[168:169], s[2:3] op_sel_hi:[1,0]
	v_pk_mul_f32 v[162:163], v[182:183], s[2:3] op_sel_hi:[1,0]
	v_pk_mul_f32 v[164:165], v[184:185], s[2:3] op_sel_hi:[1,0]
	v_pk_mul_f32 v[166:167], v[186:187], s[2:3] op_sel_hi:[1,0]
	v_exp_f32_e32 v160, v160
	v_exp_f32_e32 v161, v161
	v_exp_f32_e32 v162, v162
	v_exp_f32_e32 v163, v163
	v_exp_f32_e32 v164, v164
	v_exp_f32_e32 v165, v165
	v_exp_f32_e32 v166, v166
	v_exp_f32_e32 v167, v167
	v_pk_add_f32 v[160:161], v[160:161], s[2:3] op_sel:[0,1] op_sel_hi:[1,1]
	v_pk_add_f32 v[162:163], v[162:163], s[2:3] op_sel:[0,1] op_sel_hi:[1,1]
	v_pk_add_f32 v[164:165], v[164:165], s[2:3] op_sel:[0,1] op_sel_hi:[1,1]
	v_pk_add_f32 v[166:167], v[166:167], s[2:3] op_sel:[0,1] op_sel_hi:[1,1]
	v_rcp_f32_e32 v160, v160
	v_rcp_f32_e32 v161, v161
	v_rcp_f32_e32 v162, v162
	v_rcp_f32_e32 v163, v163
	v_rcp_f32_e32 v164, v164
	v_rcp_f32_e32 v165, v165
	v_rcp_f32_e32 v166, v166
	v_rcp_f32_e32 v167, v167
	v_pk_mul_f32 v[168:169], v[168:169], v[160:161]
	v_pk_mul_f32 v[182:183], v[182:183], v[162:163]
	v_pk_mul_f32 v[184:185], v[184:185], v[164:165]
	v_pk_mul_f32 v[186:187], v[186:187], v[166:167]
	v_pk_mul_f32 v[168:169], v[70:71], v[168:169]
	v_pk_mul_f32 v[182:183], v[72:73], v[182:183]
	v_pk_mul_f32 v[184:185], v[66:67], v[184:185]
	v_pk_mul_f32 v[186:187], v[68:69], v[186:187]
	v_cvt_pk_bf16_f32 v154, v168, v169
	v_cvt_pk_bf16_f32 v155, v182, v183
	v_cvt_pk_bf16_f32 v156, v184, v185
	v_cvt_pk_bf16_f32 v157, v186, v187
	flat_store_dwordx4 v[158:159], v[154:157]
	v_add_co_u32_e32 v158, vcc, 0x6e000, v158
	s_nop 1
	v_addc_co_u32_e32 v159, vcc, 0, v159, vcc
	s_andn2_b64 vcc, exec, s[46:47]
	s_cbranch_vccnz .Lffn_z1
	ds_read_b128 v[200:203], v228 offset:1024
	ds_read_b128 v[192:195], v228 offset:1536
	ds_read_b128 v[204:207], v228 offset:1040
	ds_read_b128 v[196:199], v228 offset:1552
	s_branch .Lffn_d1
